# EpiRes xb loads and stores coalesced (lane-transposed addresses + ds_bpermute), on top of proj+up
# speedup vs baseline: 1.0033x; 1.0033x over previous
.LBB0_455:
	s_lshl_b32 s4, s69, 8
	v_mov_b32_e32 v132, v182
	v_mov_b32_e32 v130, v183
	s_add_i32 s4, s4, s49
	s_nop 0
	v_add_u32_e32 v172, s4, v130
	v_lshrrev_b32_e32 v194, 2, v213
	v_and_b32_e32 v195, 3, v213
	v_lshlrev_b32_e32 v196, 6, v195
	v_lshl_add_u32 v196, v194, 2, v196
	v_and_b32_e32 v197, 15, v213
	v_lshlrev_b32_e32 v197, 4, v197
	v_lshrrev_b32_e32 v198, 4, v213
	v_lshl_add_u32 v197, v198, 2, v197
	v_add_u32_e32 v198, s4, v194
	v_ashrrev_i32_e32 v199, 31, v198
	s_lshl_b32 s4, s68, 8
	s_or_b32 s4, s4, s50
	v_lshl_add_u32 v130, v195, 3, s4
	v_ashrrev_i32_e32 v131, 31, v130
	v_ashrrev_i32_e32 v173, 31, v172
	v_lshlrev_b64 v[168:169], 1, v[130:131]
	v_lshl_add_u64 v[170:171], s[12:13], 0, v[168:169]
	v_lshlrev_b64 v[180:181], 11, v[198:199]
	v_lshl_add_u64 v[130:131], v[170:171], 0, v[180:181]
	global_load_dwordx4 v[188:191], v[130:131], off
	global_load_dwordx4 v[154:157], v[130:131], off offset:256
	s_lshl_b32 s4, s68, 2
	s_or_b32 s4, s4, s47
	s_ashr_i32 s5, s4, 31
	s_lshl_b64 s[30:31], s[4:5], 17
	s_mov_b64 s[4:5], 0x8000
	v_lshl_add_u64 v[178:179], v[180:181], 0, s[4:5]
	v_lshl_add_u64 v[130:131], v[170:171], 0, v[178:179]
	global_load_dwordx4 v[150:153], v[130:131], off
	global_load_dwordx4 v[146:149], v[130:131], off offset:256
	s_mov_b64 s[4:5], 0x10000
	v_lshl_add_u64 v[176:177], v[180:181], 0, s[4:5]
	v_lshl_add_u64 v[130:131], v[170:171], 0, v[176:177]
	global_load_dwordx4 v[142:145], v[130:131], off
	global_load_dwordx4 v[138:141], v[130:131], off offset:256
	s_mov_b64 s[4:5], 0x18000
	v_lshl_add_u64 v[174:175], v[180:181], 0, s[4:5]
	v_lshl_add_u64 v[130:131], v[170:171], 0, v[174:175]
	v_cmp_eq_u32_e32 vcc, 0, v132
	global_load_dwordx4 v[134:137], v[130:131], off
	s_nop 0
	global_load_dwordx4 v[130:133], v[130:131], off offset:256
	v_lshl_add_u64 v[180:181], s[12:13], 0, v[180:181]
	v_lshl_add_u64 v[180:181], v[180:181], 0, v[168:169]
	s_add_u32 s4, s14, s30
	s_addc_u32 s5, s15, s31
	s_waitcnt vmcnt(0)
	ds_bpermute_b32 v188, v197, v188
	ds_bpermute_b32 v189, v197, v189
	ds_bpermute_b32 v190, v197, v190
	ds_bpermute_b32 v191, v197, v191
	ds_bpermute_b32 v154, v197, v154
	ds_bpermute_b32 v155, v197, v155
	ds_bpermute_b32 v156, v197, v156
	ds_bpermute_b32 v157, v197, v157
	ds_bpermute_b32 v150, v197, v150
	ds_bpermute_b32 v151, v197, v151
	ds_bpermute_b32 v152, v197, v152
	ds_bpermute_b32 v153, v197, v153
	ds_bpermute_b32 v146, v197, v146
	ds_bpermute_b32 v147, v197, v147
	ds_bpermute_b32 v148, v197, v148
	ds_bpermute_b32 v149, v197, v149
	ds_bpermute_b32 v142, v197, v142
	ds_bpermute_b32 v143, v197, v143
	ds_bpermute_b32 v144, v197, v144
	ds_bpermute_b32 v145, v197, v145
	ds_bpermute_b32 v138, v197, v138
	ds_bpermute_b32 v139, v197, v139
	ds_bpermute_b32 v140, v197, v140
	ds_bpermute_b32 v141, v197, v141
	ds_bpermute_b32 v134, v197, v134
	ds_bpermute_b32 v135, v197, v135
	ds_bpermute_b32 v136, v197, v136
	ds_bpermute_b32 v137, v197, v137
	ds_bpermute_b32 v130, v197, v130
	ds_bpermute_b32 v131, v197, v131
	ds_bpermute_b32 v132, v197, v132
	ds_bpermute_b32 v133, v197, v133
	s_waitcnt lgkmcnt(0)
	v_lshlrev_b32_e32 v192, 16, v188
	v_and_b32_e32 v193, 0xffff0000, v188
	v_lshlrev_b32_e32 v188, 16, v189
	v_and_b32_e32 v189, 0xffff0000, v189
	v_pk_add_f32 v[126:127], v[126:127], v[192:193]
	v_pk_add_f32 v[128:129], v[128:129], v[188:189]
	v_cvt_pk_bf16_f32 v126, v126, v127
	v_cvt_pk_bf16_f32 v127, v128, v129
	v_lshlrev_b32_e32 v128, 16, v190
	v_and_b32_e32 v129, 0xffff0000, v190
	v_pk_add_f32 v[122:123], v[122:123], v[128:129]
	s_nop 0
	v_cvt_pk_bf16_f32 v128, v122, v123
	v_lshlrev_b32_e32 v122, 16, v191
	v_and_b32_e32 v123, 0xffff0000, v191
	v_pk_add_f32 v[122:123], v[124:125], v[122:123]
	v_and_b32_e32 v124, 0xffff0000, v127
	v_cvt_pk_bf16_f32 v129, v122, v123
	v_and_b32_e32 v123, 0xffff0000, v126
	v_lshlrev_b32_e32 v122, 16, v126
	v_mul_f32_e32 v123, v123, v123
	v_fmac_f32_e32 v123, v122, v122
	v_lshlrev_b32_e32 v122, 16, v127
	v_mul_f32_e32 v124, v124, v124
	v_fmac_f32_e32 v124, v122, v122
	v_add_f32_e32 v122, v123, v124
	v_and_b32_e32 v124, 0xffff0000, v128
	v_lshlrev_b32_e32 v123, 16, v128
	v_mul_f32_e32 v124, v124, v124
	v_fmac_f32_e32 v124, v123, v123
	v_add_f32_e32 v122, v124, v122
	v_and_b32_e32 v124, 0xffff0000, v129
	v_lshlrev_b32_e32 v123, 16, v129
	v_mul_f32_e32 v124, v124, v124
	v_fmac_f32_e32 v124, v123, v123
	v_add_f32_e32 v124, v124, v122
	v_lshlrev_b32_e32 v122, 16, v154
	v_and_b32_e32 v123, 0xffff0000, v154
	v_pk_add_f32 v[118:119], v[118:119], v[122:123]
	v_lshlrev_b32_e32 v122, 16, v155
	v_and_b32_e32 v123, 0xffff0000, v155
	v_pk_add_f32 v[120:121], v[120:121], v[122:123]
	v_cvt_pk_bf16_f32 v118, v118, v119
	v_cvt_pk_bf16_f32 v119, v120, v121
	v_lshlrev_b32_e32 v120, 16, v156
	v_and_b32_e32 v121, 0xffff0000, v156
	v_pk_add_f32 v[114:115], v[114:115], v[120:121]
	ds_bpermute_b32 v200, v196, v126
	ds_bpermute_b32 v201, v196, v127
	ds_bpermute_b32 v202, v196, v128
	ds_bpermute_b32 v203, v196, v129
	s_waitcnt lgkmcnt(0)
	global_store_dwordx4 v[180:181], v[200:203], off
	v_cvt_pk_bf16_f32 v120, v114, v115
	v_lshlrev_b32_e32 v114, 16, v157
	v_and_b32_e32 v115, 0xffff0000, v157
	v_pk_add_f32 v[114:115], v[116:117], v[114:115]
	v_and_b32_e32 v116, 0xffff0000, v119
	v_cvt_pk_bf16_f32 v121, v114, v115
	v_and_b32_e32 v115, 0xffff0000, v118
	v_lshlrev_b32_e32 v114, 16, v118
	v_mul_f32_e32 v115, v115, v115
	v_fmac_f32_e32 v115, v114, v114
	v_lshlrev_b32_e32 v114, 16, v119
	v_mul_f32_e32 v116, v116, v116
	v_fmac_f32_e32 v116, v114, v114
	v_add_f32_e32 v114, v115, v116
	v_and_b32_e32 v116, 0xffff0000, v120
	v_lshlrev_b32_e32 v115, 16, v120
	v_mul_f32_e32 v116, v116, v116
	v_fmac_f32_e32 v116, v115, v115
	v_add_f32_e32 v114, v116, v114
	v_and_b32_e32 v116, 0xffff0000, v121
	v_lshlrev_b32_e32 v115, 16, v121
	v_mul_f32_e32 v116, v116, v116
	v_fmac_f32_e32 v116, v115, v115
	v_add_f32_e32 v114, v116, v114
	v_lshlrev_b32_e32 v116, 16, v150
	v_and_b32_e32 v117, 0xffff0000, v150
	v_pk_add_f32 v[110:111], v[110:111], v[116:117]
	v_lshlrev_b32_e32 v116, 16, v151
	v_and_b32_e32 v117, 0xffff0000, v151
	v_pk_add_f32 v[112:113], v[112:113], v[116:117]
	v_cvt_pk_bf16_f32 v110, v110, v111
	v_cvt_pk_bf16_f32 v111, v112, v113
	v_lshlrev_b32_e32 v112, 16, v152
	v_and_b32_e32 v113, 0xffff0000, v152
	v_pk_add_f32 v[106:107], v[106:107], v[112:113]
	ds_bpermute_b32 v200, v196, v118
	ds_bpermute_b32 v201, v196, v119
	ds_bpermute_b32 v202, v196, v120
	ds_bpermute_b32 v203, v196, v121
	s_waitcnt lgkmcnt(0)
	global_store_dwordx4 v[180:181], v[200:203], off offset:256
	v_cvt_pk_bf16_f32 v112, v106, v107
	v_lshlrev_b32_e32 v106, 16, v153
	v_and_b32_e32 v107, 0xffff0000, v153
	v_pk_add_f32 v[106:107], v[108:109], v[106:107]
	v_add_f32_e32 v118, v124, v114
	v_cvt_pk_bf16_f32 v113, v106, v107
	v_lshlrev_b32_e32 v106, 16, v146
	v_and_b32_e32 v107, 0xffff0000, v146
	v_pk_add_f32 v[102:103], v[102:103], v[106:107]
	v_lshlrev_b32_e32 v106, 16, v147
	v_and_b32_e32 v107, 0xffff0000, v147
	v_pk_add_f32 v[104:105], v[104:105], v[106:107]
	v_cvt_pk_bf16_f32 v102, v102, v103
	v_cvt_pk_bf16_f32 v103, v104, v105
	v_lshlrev_b32_e32 v104, 16, v148
	v_and_b32_e32 v105, 0xffff0000, v148
	v_pk_add_f32 v[94:95], v[94:95], v[104:105]
	v_lshl_add_u64 v[114:115], s[12:13], 0, v[178:179]
	v_cvt_pk_bf16_f32 v104, v94, v95
	v_lshlrev_b32_e32 v94, 16, v149
	v_and_b32_e32 v95, 0xffff0000, v149
	v_pk_add_f32 v[94:95], v[96:97], v[94:95]
	v_lshlrev_b32_e32 v96, 16, v143
	v_cvt_pk_bf16_f32 v105, v94, v95
	v_lshl_add_u64 v[94:95], s[12:13], 0, v[176:177]
	v_lshl_add_u64 v[106:107], v[94:95], 0, v[168:169]
	v_lshlrev_b32_e32 v94, 16, v142
	v_and_b32_e32 v95, 0xffff0000, v142
	v_and_b32_e32 v97, 0xffff0000, v143
	v_pk_add_f32 v[94:95], v[98:99], v[94:95]
	v_pk_add_f32 v[96:97], v[100:101], v[96:97]
	v_cvt_pk_bf16_f32 v94, v94, v95
	v_cvt_pk_bf16_f32 v95, v96, v97
	v_lshlrev_b32_e32 v96, 16, v144
	v_and_b32_e32 v97, 0xffff0000, v144
	v_pk_add_f32 v[90:91], v[90:91], v[96:97]
	v_lshl_add_u64 v[114:115], v[114:115], 0, v[168:169]
	v_cvt_pk_bf16_f32 v96, v90, v91
	v_lshlrev_b32_e32 v90, 16, v145
	v_and_b32_e32 v91, 0xffff0000, v145
	v_pk_add_f32 v[90:91], v[92:93], v[90:91]
	v_lshl_add_u64 v[98:99], v[172:173], 2, s[4:5]
	v_cvt_pk_bf16_f32 v97, v90, v91
	v_lshlrev_b32_e32 v90, 16, v138
	v_and_b32_e32 v91, 0xffff0000, v138
	v_pk_add_f32 v[86:87], v[86:87], v[90:91]
	v_lshlrev_b32_e32 v90, 16, v139
	v_and_b32_e32 v91, 0xffff0000, v139
	v_pk_add_f32 v[88:89], v[88:89], v[90:91]
	v_cvt_pk_bf16_f32 v86, v86, v87
	v_cvt_pk_bf16_f32 v87, v88, v89
	v_lshlrev_b32_e32 v88, 16, v140
	v_and_b32_e32 v89, 0xffff0000, v140
	v_pk_add_f32 v[78:79], v[78:79], v[88:89]
	ds_bpermute_b32 v200, v196, v110
	ds_bpermute_b32 v201, v196, v111
	ds_bpermute_b32 v202, v196, v112
	ds_bpermute_b32 v203, v196, v113
	s_waitcnt lgkmcnt(0)
	global_store_dwordx4 v[114:115], v[200:203], off
	v_cvt_pk_bf16_f32 v88, v78, v79
	v_lshlrev_b32_e32 v78, 16, v141
	v_and_b32_e32 v79, 0xffff0000, v141
	v_pk_add_f32 v[78:79], v[80:81], v[78:79]
	v_lshlrev_b32_e32 v80, 16, v135
	v_cvt_pk_bf16_f32 v89, v78, v79
	v_lshl_add_u64 v[78:79], s[12:13], 0, v[174:175]
	v_lshl_add_u64 v[90:91], v[78:79], 0, v[168:169]
	v_lshlrev_b32_e32 v78, 16, v134
	v_and_b32_e32 v79, 0xffff0000, v134
	v_and_b32_e32 v81, 0xffff0000, v135
	v_pk_add_f32 v[78:79], v[82:83], v[78:79]
	v_pk_add_f32 v[80:81], v[84:85], v[80:81]
	v_cvt_pk_bf16_f32 v78, v78, v79
	v_cvt_pk_bf16_f32 v79, v80, v81
	v_lshlrev_b32_e32 v80, 16, v136
	v_and_b32_e32 v81, 0xffff0000, v136
	v_pk_add_f32 v[74:75], v[74:75], v[80:81]
	ds_bpermute_b32 v200, v196, v102
	ds_bpermute_b32 v201, v196, v103
	ds_bpermute_b32 v202, v196, v104
	ds_bpermute_b32 v203, v196, v105
	s_waitcnt lgkmcnt(0)
	global_store_dwordx4 v[114:115], v[200:203], off offset:256
	v_cvt_pk_bf16_f32 v80, v74, v75
	v_lshlrev_b32_e32 v74, 16, v137
	v_and_b32_e32 v75, 0xffff0000, v137
	v_pk_add_f32 v[74:75], v[76:77], v[74:75]
	ds_bpermute_b32 v200, v196, v94
	ds_bpermute_b32 v201, v196, v95
	ds_bpermute_b32 v202, v196, v96
	ds_bpermute_b32 v203, v196, v97
	s_waitcnt lgkmcnt(0)
	global_store_dwordx4 v[106:107], v[200:203], off
	v_cvt_pk_bf16_f32 v81, v74, v75
	v_lshlrev_b32_e32 v74, 16, v130
	v_and_b32_e32 v75, 0xffff0000, v130
	v_pk_add_f32 v[70:71], v[70:71], v[74:75]
	v_lshlrev_b32_e32 v74, 16, v131
	v_and_b32_e32 v75, 0xffff0000, v131
	v_pk_add_f32 v[72:73], v[72:73], v[74:75]
	v_cvt_pk_bf16_f32 v70, v70, v71
	v_cvt_pk_bf16_f32 v71, v72, v73
	v_lshlrev_b32_e32 v72, 16, v132
	v_and_b32_e32 v73, 0xffff0000, v132
	v_pk_add_f32 v[66:67], v[66:67], v[72:73]
	ds_bpermute_b32 v200, v196, v86
	ds_bpermute_b32 v201, v196, v87
	ds_bpermute_b32 v202, v196, v88
	ds_bpermute_b32 v203, v196, v89
	s_waitcnt lgkmcnt(0)
	global_store_dwordx4 v[106:107], v[200:203], off offset:256
	v_cvt_pk_bf16_f32 v72, v66, v67
	v_lshlrev_b32_e32 v66, 16, v133
	v_and_b32_e32 v67, 0xffff0000, v133
	v_pk_add_f32 v[66:67], v[68:69], v[66:67]
	ds_bpermute_b32 v200, v196, v78
	ds_bpermute_b32 v201, v196, v79
	ds_bpermute_b32 v202, v196, v80
	ds_bpermute_b32 v203, v196, v81
	s_waitcnt lgkmcnt(0)
	global_store_dwordx4 v[90:91], v[200:203], off
	v_cvt_pk_bf16_f32 v73, v66, v67
	ds_bpermute_b32 v66, v185, v118
	ds_bpermute_b32 v200, v196, v70
	ds_bpermute_b32 v201, v196, v71
	ds_bpermute_b32 v202, v196, v72
	ds_bpermute_b32 v203, v196, v73
	s_waitcnt lgkmcnt(0)
	global_store_dwordx4 v[90:91], v[200:203], off offset:256
	s_waitcnt lgkmcnt(0)
	v_add_f32_e32 v66, v118, v66
	ds_bpermute_b32 v67, v186, v66
	s_and_saveexec_b64 s[30:31], vcc
	s_cbranch_execz .LBB0_457
	s_waitcnt lgkmcnt(0)
	v_add_f32_e32 v66, v66, v67
	global_store_dword v[98:99], v66, off

.LBB0_463:
	s_or_b64 exec, exec, s[30:31]
	s_waitcnt lgkmcnt(0)
	v_lshlrev_b64 v[66:67], 11, v[198:199]
	s_mov_b64 s[4:5], 0x40000
	v_lshl_add_u64 v[102:103], v[66:67], 0, s[4:5]
	v_lshl_add_u64 v[68:69], v[170:171], 0, v[102:103]
	global_load_dwordx4 v[104:107], v[68:69], off
	global_load_dwordx4 v[90:93], v[68:69], off offset:256
	s_mov_b64 s[4:5], 0x48000
	v_lshl_add_u64 v[100:101], v[66:67], 0, s[4:5]
	v_lshl_add_u64 v[68:69], v[170:171], 0, v[100:101]
	global_load_dwordx4 v[86:89], v[68:69], off
	global_load_dwordx4 v[82:85], v[68:69], off offset:256
	s_mov_b64 s[4:5], 0x50000
	v_lshl_add_u64 v[96:97], v[66:67], 0, s[4:5]
	v_lshl_add_u64 v[68:69], v[170:171], 0, v[96:97]
	global_load_dwordx4 v[78:81], v[68:69], off
	global_load_dwordx4 v[70:73], v[68:69], off offset:256
	s_mov_b64 s[4:5], 0x58000
	v_lshl_add_u64 v[94:95], v[66:67], 0, s[4:5]
	v_lshl_add_u64 v[66:67], v[170:171], 0, v[94:95]
	global_load_dwordx4 v[74:77], v[66:67], off
	s_nop 0
	global_load_dwordx4 v[66:69], v[66:67], off offset:256
	v_lshl_add_u64 v[102:103], s[12:13], 0, v[102:103]
	v_lshl_add_u64 v[102:103], v[102:103], 0, v[168:169]
	s_waitcnt vmcnt(0)
	ds_bpermute_b32 v104, v197, v104
	ds_bpermute_b32 v105, v197, v105
	ds_bpermute_b32 v106, v197, v106
	ds_bpermute_b32 v107, v197, v107
	ds_bpermute_b32 v90, v197, v90
	ds_bpermute_b32 v91, v197, v91
	ds_bpermute_b32 v92, v197, v92
	ds_bpermute_b32 v93, v197, v93
	ds_bpermute_b32 v86, v197, v86
	ds_bpermute_b32 v87, v197, v87
	ds_bpermute_b32 v88, v197, v88
	ds_bpermute_b32 v89, v197, v89
	ds_bpermute_b32 v82, v197, v82
	ds_bpermute_b32 v83, v197, v83
	ds_bpermute_b32 v84, v197, v84
	ds_bpermute_b32 v85, v197, v85
	ds_bpermute_b32 v78, v197, v78
	ds_bpermute_b32 v79, v197, v79
	ds_bpermute_b32 v80, v197, v80
	ds_bpermute_b32 v81, v197, v81
	ds_bpermute_b32 v70, v197, v70
	ds_bpermute_b32 v71, v197, v71
	ds_bpermute_b32 v72, v197, v72
	ds_bpermute_b32 v73, v197, v73
	ds_bpermute_b32 v74, v197, v74
	ds_bpermute_b32 v75, v197, v75
	ds_bpermute_b32 v76, v197, v76
	ds_bpermute_b32 v77, v197, v77
	ds_bpermute_b32 v66, v197, v66
	ds_bpermute_b32 v67, v197, v67
	ds_bpermute_b32 v68, v197, v68
	ds_bpermute_b32 v69, v197, v69
	s_waitcnt lgkmcnt(0)
	v_lshlrev_b32_e32 v108, 16, v104
	v_and_b32_e32 v109, 0xffff0000, v104
	v_lshlrev_b32_e32 v104, 16, v105
	v_and_b32_e32 v105, 0xffff0000, v105
	v_pk_add_f32 v[62:63], v[62:63], v[108:109]
	v_pk_add_f32 v[64:65], v[64:65], v[104:105]
	v_cvt_pk_bf16_f32 v62, v62, v63
	v_cvt_pk_bf16_f32 v63, v64, v65
	v_lshlrev_b32_e32 v64, 16, v106
	v_and_b32_e32 v65, 0xffff0000, v106
	v_pk_add_f32 v[58:59], v[58:59], v[64:65]
	s_nop 0
	v_cvt_pk_bf16_f32 v64, v58, v59
	v_lshlrev_b32_e32 v58, 16, v107
	v_and_b32_e32 v59, 0xffff0000, v107
	v_pk_add_f32 v[58:59], v[60:61], v[58:59]
	v_and_b32_e32 v60, 0xffff0000, v63
	v_cvt_pk_bf16_f32 v65, v58, v59
	v_and_b32_e32 v59, 0xffff0000, v62
	v_lshlrev_b32_e32 v58, 16, v62
	v_mul_f32_e32 v59, v59, v59
	v_fmac_f32_e32 v59, v58, v58
	v_lshlrev_b32_e32 v58, 16, v63
	v_mul_f32_e32 v60, v60, v60
	v_fmac_f32_e32 v60, v58, v58
	v_add_f32_e32 v58, v59, v60
	v_and_b32_e32 v60, 0xffff0000, v64
	v_lshlrev_b32_e32 v59, 16, v64
	v_mul_f32_e32 v60, v60, v60
	v_fmac_f32_e32 v60, v59, v59
	v_add_f32_e32 v58, v60, v58
	v_and_b32_e32 v60, 0xffff0000, v65
	v_lshlrev_b32_e32 v59, 16, v65
	v_mul_f32_e32 v60, v60, v60
	v_fmac_f32_e32 v60, v59, v59
	v_add_f32_e32 v60, v60, v58
	s_waitcnt vmcnt(6)
	v_lshlrev_b32_e32 v58, 16, v90
	v_and_b32_e32 v59, 0xffff0000, v90
	v_pk_add_f32 v[54:55], v[54:55], v[58:59]
	v_lshlrev_b32_e32 v58, 16, v91
	v_and_b32_e32 v59, 0xffff0000, v91
	v_pk_add_f32 v[56:57], v[56:57], v[58:59]
	v_cvt_pk_bf16_f32 v54, v54, v55
	v_cvt_pk_bf16_f32 v55, v56, v57
	v_lshlrev_b32_e32 v56, 16, v92
	v_and_b32_e32 v57, 0xffff0000, v92
	v_pk_add_f32 v[50:51], v[50:51], v[56:57]
	ds_bpermute_b32 v200, v196, v62
	ds_bpermute_b32 v201, v196, v63
	ds_bpermute_b32 v202, v196, v64
	ds_bpermute_b32 v203, v196, v65
	s_waitcnt lgkmcnt(0)
	global_store_dwordx4 v[102:103], v[200:203], off
	v_cvt_pk_bf16_f32 v56, v50, v51
	v_lshlrev_b32_e32 v50, 16, v93
	v_and_b32_e32 v51, 0xffff0000, v93
	v_pk_add_f32 v[50:51], v[52:53], v[50:51]
	v_and_b32_e32 v52, 0xffff0000, v55
	v_cvt_pk_bf16_f32 v57, v50, v51
	v_and_b32_e32 v51, 0xffff0000, v54
	v_lshlrev_b32_e32 v50, 16, v54
	v_mul_f32_e32 v51, v51, v51
	v_fmac_f32_e32 v51, v50, v50
	v_lshlrev_b32_e32 v50, 16, v55
	v_mul_f32_e32 v52, v52, v52
	v_fmac_f32_e32 v52, v50, v50
	v_add_f32_e32 v50, v51, v52
	v_and_b32_e32 v52, 0xffff0000, v56
	v_lshlrev_b32_e32 v51, 16, v56
	v_mul_f32_e32 v52, v52, v52
	v_fmac_f32_e32 v52, v51, v51
	v_add_f32_e32 v50, v52, v50
	v_and_b32_e32 v52, 0xffff0000, v57
	v_lshlrev_b32_e32 v51, 16, v57
	v_mul_f32_e32 v52, v52, v52
	v_fmac_f32_e32 v52, v51, v51
	v_add_f32_e32 v50, v52, v50
	s_waitcnt vmcnt(6)
	v_lshlrev_b32_e32 v52, 16, v86
	v_and_b32_e32 v53, 0xffff0000, v86
	v_pk_add_f32 v[46:47], v[46:47], v[52:53]
	v_lshlrev_b32_e32 v52, 16, v87
	v_and_b32_e32 v53, 0xffff0000, v87
	v_pk_add_f32 v[48:49], v[48:49], v[52:53]
	v_cvt_pk_bf16_f32 v46, v46, v47
	v_cvt_pk_bf16_f32 v47, v48, v49
	v_lshlrev_b32_e32 v48, 16, v88
	v_and_b32_e32 v49, 0xffff0000, v88
	v_pk_add_f32 v[42:43], v[42:43], v[48:49]
	ds_bpermute_b32 v200, v196, v54
	ds_bpermute_b32 v201, v196, v55
	ds_bpermute_b32 v202, v196, v56
	ds_bpermute_b32 v203, v196, v57
	s_waitcnt lgkmcnt(0)
	global_store_dwordx4 v[102:103], v[200:203], off offset:256
	v_cvt_pk_bf16_f32 v48, v42, v43
	v_lshlrev_b32_e32 v42, 16, v89
	v_and_b32_e32 v43, 0xffff0000, v89
	v_pk_add_f32 v[42:43], v[44:45], v[42:43]
	v_add_f32_e32 v54, v60, v50
	v_cvt_pk_bf16_f32 v49, v42, v43
	s_waitcnt vmcnt(6)
	v_lshlrev_b32_e32 v42, 16, v82
	v_and_b32_e32 v43, 0xffff0000, v82
	v_pk_add_f32 v[38:39], v[38:39], v[42:43]
	v_lshlrev_b32_e32 v42, 16, v83
	v_and_b32_e32 v43, 0xffff0000, v83
	v_pk_add_f32 v[40:41], v[40:41], v[42:43]
	v_cvt_pk_bf16_f32 v38, v38, v39
	v_cvt_pk_bf16_f32 v39, v40, v41
	v_lshlrev_b32_e32 v40, 16, v84
	v_and_b32_e32 v41, 0xffff0000, v84
	v_pk_add_f32 v[30:31], v[30:31], v[40:41]
	v_lshl_add_u64 v[50:51], s[12:13], 0, v[100:101]
	v_cvt_pk_bf16_f32 v40, v30, v31
	v_lshlrev_b32_e32 v30, 16, v85
	v_and_b32_e32 v31, 0xffff0000, v85
	v_pk_add_f32 v[30:31], v[32:33], v[30:31]
	s_waitcnt vmcnt(5)
	v_lshlrev_b32_e32 v32, 16, v79
	v_cvt_pk_bf16_f32 v41, v30, v31
	v_lshl_add_u64 v[30:31], s[12:13], 0, v[96:97]
	v_lshl_add_u64 v[42:43], v[30:31], 0, v[168:169]
	v_lshlrev_b32_e32 v30, 16, v78
	v_and_b32_e32 v31, 0xffff0000, v78
	v_and_b32_e32 v33, 0xffff0000, v79
	v_pk_add_f32 v[30:31], v[34:35], v[30:31]
	v_pk_add_f32 v[32:33], v[36:37], v[32:33]
	v_cvt_pk_bf16_f32 v30, v30, v31
	v_cvt_pk_bf16_f32 v31, v32, v33
	v_lshlrev_b32_e32 v32, 16, v80
	v_and_b32_e32 v33, 0xffff0000, v80
	v_pk_add_f32 v[26:27], v[26:27], v[32:33]
	v_lshl_add_u64 v[50:51], v[50:51], 0, v[168:169]
	v_cvt_pk_bf16_f32 v32, v26, v27
	v_lshlrev_b32_e32 v26, 16, v81
	v_and_b32_e32 v27, 0xffff0000, v81
	v_pk_add_f32 v[26:27], v[28:29], v[26:27]
	ds_bpermute_b32 v200, v196, v46
	ds_bpermute_b32 v201, v196, v47
	ds_bpermute_b32 v202, v196, v48
	ds_bpermute_b32 v203, v196, v49
	s_waitcnt lgkmcnt(0)
	global_store_dwordx4 v[50:51], v[200:203], off
	v_cvt_pk_bf16_f32 v33, v26, v27
	s_waitcnt vmcnt(5)
	v_lshlrev_b32_e32 v26, 16, v70
	v_and_b32_e32 v27, 0xffff0000, v70
	v_pk_add_f32 v[22:23], v[22:23], v[26:27]
	v_lshlrev_b32_e32 v26, 16, v71
	v_and_b32_e32 v27, 0xffff0000, v71
	v_pk_add_f32 v[24:25], v[24:25], v[26:27]
	v_cvt_pk_bf16_f32 v22, v22, v23
	v_cvt_pk_bf16_f32 v23, v24, v25
	v_lshlrev_b32_e32 v24, 16, v72
	v_and_b32_e32 v25, 0xffff0000, v72
	v_pk_add_f32 v[14:15], v[14:15], v[24:25]
	ds_bpermute_b32 v200, v196, v38
	ds_bpermute_b32 v201, v196, v39
	ds_bpermute_b32 v202, v196, v40
	ds_bpermute_b32 v203, v196, v41
	s_waitcnt lgkmcnt(0)
	global_store_dwordx4 v[50:51], v[200:203], off offset:256
	v_cvt_pk_bf16_f32 v24, v14, v15
	v_lshlrev_b32_e32 v14, 16, v73
	v_and_b32_e32 v15, 0xffff0000, v73
	v_pk_add_f32 v[14:15], v[16:17], v[14:15]
	s_waitcnt vmcnt(5)
	v_lshlrev_b32_e32 v16, 16, v75
	v_cvt_pk_bf16_f32 v25, v14, v15
	v_lshl_add_u64 v[14:15], s[12:13], 0, v[94:95]
	v_lshl_add_u64 v[26:27], v[14:15], 0, v[168:169]
	v_lshlrev_b32_e32 v14, 16, v74
	v_and_b32_e32 v15, 0xffff0000, v74
	v_and_b32_e32 v17, 0xffff0000, v75
	v_pk_add_f32 v[14:15], v[18:19], v[14:15]
	v_pk_add_f32 v[16:17], v[20:21], v[16:17]
	v_cvt_pk_bf16_f32 v14, v14, v15
	v_cvt_pk_bf16_f32 v15, v16, v17
	v_lshlrev_b32_e32 v16, 16, v76
	v_and_b32_e32 v17, 0xffff0000, v76
	v_pk_add_f32 v[10:11], v[10:11], v[16:17]
	ds_bpermute_b32 v200, v196, v30
	ds_bpermute_b32 v201, v196, v31
	ds_bpermute_b32 v202, v196, v32
	ds_bpermute_b32 v203, v196, v33
	s_waitcnt lgkmcnt(0)
	global_store_dwordx4 v[42:43], v[200:203], off
	v_cvt_pk_bf16_f32 v16, v10, v11
	v_lshlrev_b32_e32 v10, 16, v77
	v_and_b32_e32 v11, 0xffff0000, v77
	v_pk_add_f32 v[10:11], v[12:13], v[10:11]
	ds_bpermute_b32 v200, v196, v22
	ds_bpermute_b32 v201, v196, v23
	ds_bpermute_b32 v202, v196, v24
	ds_bpermute_b32 v203, v196, v25
	s_waitcnt lgkmcnt(0)
	global_store_dwordx4 v[42:43], v[200:203], off offset:256
	v_cvt_pk_bf16_f32 v17, v10, v11
	s_waitcnt vmcnt(6)
	v_lshlrev_b32_e32 v10, 16, v66
	v_and_b32_e32 v11, 0xffff0000, v66
	v_pk_add_f32 v[6:7], v[6:7], v[10:11]
	v_lshlrev_b32_e32 v10, 16, v67
	v_and_b32_e32 v11, 0xffff0000, v67
	v_pk_add_f32 v[8:9], v[8:9], v[10:11]
	v_cvt_pk_bf16_f32 v6, v6, v7
	v_cvt_pk_bf16_f32 v7, v8, v9
	v_lshlrev_b32_e32 v8, 16, v68
	v_and_b32_e32 v9, 0xffff0000, v68
	v_pk_add_f32 v[2:3], v[2:3], v[8:9]
	ds_bpermute_b32 v200, v196, v14
	ds_bpermute_b32 v201, v196, v15
	ds_bpermute_b32 v202, v196, v16
	ds_bpermute_b32 v203, v196, v17
	s_waitcnt lgkmcnt(0)
	global_store_dwordx4 v[26:27], v[200:203], off
	v_cvt_pk_bf16_f32 v8, v2, v3
	v_lshlrev_b32_e32 v2, 16, v69
	v_and_b32_e32 v3, 0xffff0000, v69
	v_pk_add_f32 v[2:3], v[4:5], v[2:3]
	s_nop 0
	v_cvt_pk_bf16_f32 v9, v2, v3
	ds_bpermute_b32 v2, v185, v54
	ds_bpermute_b32 v200, v196, v6
	ds_bpermute_b32 v201, v196, v7
	ds_bpermute_b32 v202, v196, v8
	ds_bpermute_b32 v203, v196, v9
	s_waitcnt lgkmcnt(0)
	global_store_dwordx4 v[26:27], v[200:203], off offset:256
	s_waitcnt lgkmcnt(0)
	v_add_f32_e32 v2, v54, v2
	ds_bpermute_b32 v3, v186, v2
	s_and_saveexec_b64 s[30:31], vcc
	s_cbranch_execz .LBB0_465
	s_waitcnt lgkmcnt(0)
	v_add_f32_e32 v2, v2, v3
	global_store_dword v[98:99], v2, off offset:512
